# instruction-side warm-up: at every grid barrier wave 1 touches the first 32 KiB of the next phase's code (PC-relative data loads) so post-barrier instruction fetches hit L2; stacked on v85
# baseline (speedup 1.0000x reference)
.LBB0_188:
	s_or_b64 exec, exec, s[4:5]
	v_readlane_b32 s98, v254, 61
	s_cmp_lg_u32 s98, 1
	s_cbranch_scc1 .Lcpf_skip_0
	s_getpc_b64 s[98:99]
.Lcpf_pc_0:
	s_add_u32 s98, s98, .LBB0_189-.Lcpf_pc_0
	s_addc_u32 s99, s99, 0
	v_lshlrev_b32_e32 v252, 7, v186
	global_load_dword v253, v252, s[98:99]
	s_add_u32 s98, s98, 0x2000
	s_addc_u32 s99, s99, 0
	global_load_dword v253, v252, s[98:99]
	s_add_u32 s98, s98, 0x2000
	s_addc_u32 s99, s99, 0
	global_load_dword v253, v252, s[98:99]
	s_add_u32 s98, s98, 0x2000
	s_addc_u32 s99, s99, 0
	global_load_dword v253, v252, s[98:99]
.Lcpf_skip_0:
	s_waitcnt lgkmcnt(0)
	s_barrier
.LBB0_189:
	s_cmp_lt_i32 s52, 2
	s_cselect_b64 s[20:21], -1, 0
	s_add_u32 s2, s70, 0x5400000
	s_addc_u32 s3, s71, 0
	v_writelane_b32 v255, s2, 0
	s_nop 1
	v_writelane_b32 v255, s3, 1
	s_add_u32 s2, s68, 0xb00000
	s_addc_u32 s3, s69, 0
	v_writelane_b32 v255, s2, 2
	s_and_b64 s[0:1], s[20:21], s[0:1]
	s_andn2_b64 vcc, exec, s[0:1]
	v_writelane_b32 v255, s3, 3
	v_writelane_b32 v255, s97, 4
	v_writelane_b32 v255, s54, 5
	v_writelane_b32 v255, s56, 6
	v_writelane_b32 v255, s52, 7
	s_nop 1
	v_writelane_b32 v255, s53, 8
	v_writelane_b32 v255, s57, 9
	v_writelane_b32 v255, s33, 10
	s_cbranch_vccnz .LBB0_290
	s_abs_i32 s22, s54
	v_cvt_f32_u32_e32 v2, s22
	s_sub_i32 s0, 0, s22
	v_rcp_iflag_f32_e32 v2, v2
	s_nop 0
	v_mul_f32_e32 v2, 0x4f7ffffe, v2
	v_cvt_u32_f32_e32 v2, v2
	s_nop 0
	v_readfirstlane_b32 s1, v2
	s_mul_i32 s0, s0, s1
	s_mul_hi_u32 s0, s1, s0
	s_add_i32 s1, s1, s0
	s_mul_hi_u32 s23, s1, 0x5d8
	s_cmpk_gt_i32 s56, 0x5d7
	v_readfirstlane_b32 s1, v0
	s_cbranch_scc1 .LBB0_213
	v_lshlrev_b32_e32 v2, 4, v0
	v_and_b32_e32 v3, 32, v0
	v_lshrrev_b32_e32 v4, 3, v0
	s_waitcnt vmcnt(4)
	v_bfe_u32 v6, v0, 2, 4
	v_lshrrev_b32_e32 v9, 1, v0
	v_lshrrev_b32_e32 v10, 5, v0
	v_bfe_u32 v11, v0, 2, 2
	v_and_or_b32 v5, v4, 48, v6
	v_bitop3_b32 v7, v2, v3, 48 bitop3:0x6c
	v_and_b32_e32 v8, 64, v0
	v_and_b32_e32 v4, 32, v4
	v_and_b32_e32 v9, 24, v9
	v_and_or_b32 v10, v10, 4, v11
	s_movk_i32 s0, 0x60
	s_ashr_i32 s52, s56, 31
	v_or3_b32 v4, v10, v4, v9
	v_bitop3_b32 v10, v7, s0, v8 bitop3:0xc8
	s_lshr_b32 s0, s52, 29
	s_add_i32 s0, s56, s0
	s_lshr_b32 s3, s1, 6
	s_ashr_i32 s4, s0, 3
	s_and_b32 s0, s0, -8
	s_lshr_b32 s2, s1, 8
	s_lshl_b32 s51, s3, 10
	s_sub_i32 s0, s56, s0
	s_cmp_lt_i32 s0, 0
	s_movk_i32 s5, 0xbc
	s_cselect_b32 s5, s5, 0xbb
	s_mul_i32 s0, s0, s5
	s_add_i32 s0, s0, s4
	s_mul_hi_i32 s4, s0, 0x2e8ba2e9
	s_lshr_b32 s5, s4, 31
	s_ashr_i32 s4, s4, 5
	s_add_i32 s4, s4, s5
	s_lshl_b32 s6, s4, 3
	s_sub_i32 s5, 0x44, s6
	s_mulk_i32 s4, 0xb0
	v_or_b32_e32 v3, v7, v8
	s_min_u32 s7, s5, 8
	s_sub_i32 s8, s0, s4
	v_lshl_or_b32 v132, v4, 11, v3
	s_sext_i32_i16 s0, s8
	v_cvt_f32_ubyte0_e32 v3, s7
	v_and_b32_e32 v9, 16, v2
	v_cvt_f32_i32_e32 v2, s0
	v_rcp_iflag_f32_e32 v4, v3
	s_ashr_i32 s0, s0, 30
	s_or_b32 s0, s0, 1
	v_and_b32_e32 v142, 0xff, v0
	v_mul_f32_e32 v4, v2, v4
	v_trunc_f32_e32 v4, v4
	v_fma_f32 v2, -v4, v3, v2
	v_cvt_i32_f32_e32 v4, v4
	v_cmp_ge_f32_e64 s[4:5], |v2|, v3
	s_and_b64 s[4:5], s[4:5], exec
	s_cselect_b32 s0, s0, 0
	v_readfirstlane_b32 s4, v4
	s_add_i32 s0, s4, s0
	s_mul_i32 s4, s0, s7
	s_sub_i32 s4, s8, s4
	s_sext_i32_i16 s4, s4
	s_add_i32 s10, s6, s4
	v_readfirstlane_b32 s4, v0
	s_lshl_b32 s4, s4, 4
	s_and_b32 s4, s4, 0xc00
	s_add_i32 s4, s4, 0
	s_ashr_i32 s11, s10, 31
	s_add_i32 m0, s4, 0x22000
	s_lshl_b64 s[4:5], s[10:11], 19
	v_readlane_b32 s6, v254, 62
	v_readlane_b32 s7, v254, 63
	s_add_u32 s24, s6, s4
	s_addc_u32 s25, s7, s5
	s_bfe_i64 s[4:5], s[0:1], 0x100000
	v_lshl_or_b32 v2, s10, 8, v142
	s_lshl_b64 s[4:5], s[4:5], 19
	v_ashrrev_i32_e32 v3, 31, v2
	s_add_u32 s6, s68, s4
	v_mov_b32_e32 v133, 0
	v_lshl_add_u64 v[2:3], v[2:3], 4, s[60:61]
	s_addc_u32 s7, s69, s5
	s_add_i32 s11, s51, 0
	v_lshlrev_b32_e32 v5, 11, v5
	global_load_lds_dwordx4 v[2:3], off
	v_lshl_add_u64 v[2:3], s[6:7], 0, v[132:133]
	s_add_i32 m0, s11, 0x10000
	s_mov_b64 s[26:27], 0x20000
	v_or3_b32 v130, v10, v5, v9
	global_load_lds_dwordx4 v132, s[6:7]
	v_lshl_add_u64 v[4:5], v[2:3], 0, s[26:27]
	s_add_i32 m0, s11, 0x12000
	s_mov_b64 s[28:29], 0x40000
	global_load_lds_dwordx4 v[4:5], off
	v_lshl_add_u64 v[4:5], v[2:3], 0, s[28:29]
	s_add_i32 m0, s11, 0x14000
	s_mov_b64 s[30:31], 0x60000
	v_mov_b32_e32 v131, v133
	global_load_lds_dwordx4 v[4:5], off
	v_lshl_add_u64 v[4:5], v[2:3], 0, s[30:31]
	s_add_i32 m0, s11, 0x16000
	s_add_i32 s54, s11, 0x2000
	global_load_lds_dwordx4 v[4:5], off
	v_lshl_add_u64 v[4:5], s[24:25], 0, v[130:131]
	s_mov_b32 m0, s11
	v_lshl_add_u64 v[10:11], v[4:5], 0, s[26:27]
	global_load_lds_dwordx4 v130, s[24:25]
	s_mov_b32 m0, s54
	s_add_i32 s55, s11, 0x4000
	global_load_lds_dwordx4 v[10:11], off
	v_lshl_add_u64 v[10:11], v[4:5], 0, s[28:29]
	s_mov_b32 m0, s55
	s_add_i32 s56, s11, 0x6000
	global_load_lds_dwordx4 v[10:11], off
	v_lshl_add_u64 v[10:11], v[4:5], 0, s[30:31]
	s_mov_b32 m0, s56
	v_writelane_b32 v255, s58, 11
	global_load_lds_dwordx4 v[10:11], off
	s_cmp_eq_u32 s2, 1
	v_writelane_b32 v255, s59, 12
	s_cselect_b64 s[4:5], -1, 0
	v_writelane_b32 v255, s4, 13
	s_movk_i32 s16, 0xbc
	s_mov_b64 s[18:19], s[60:61]
	v_writelane_b32 v255, s5, 14
	s_cmp_lg_u32 s2, 1
	s_cbranch_scc1 .LBB0_193
	s_barrier

.Lcpf_skip_1:
	s_waitcnt lgkmcnt(0)
	s_barrier
.LBB0_340:
	s_cmp_lt_i32 s52, 3
	s_cselect_b64 s[22:23], -1, 0
	s_add_u32 s2, s70, 0xd00000
	s_addc_u32 s3, s71, 0
	v_writelane_b32 v255, s2, 15
	s_nop 1
	v_writelane_b32 v255, s3, 16
	s_add_u32 s2, s70, 0x1800000
	s_addc_u32 s3, s71, 0
	v_writelane_b32 v255, s2, 13
	s_nop 1
	v_writelane_b32 v255, s3, 14
	s_add_u32 s2, s70, 0x1d80000
	s_addc_u32 s3, s71, 0
	v_writelane_b32 v255, s2, 17
	s_nop 1
	v_writelane_b32 v255, s3, 18
	s_add_u32 s2, s70, 0x2980000
	s_addc_u32 s3, s71, 0
	v_writelane_b32 v255, s2, 19
	s_nop 1
	v_writelane_b32 v255, s3, 20
	s_add_u32 s2, s70, 0x2b80000
	s_addc_u32 s3, s71, 0
	v_writelane_b32 v255, s2, 21
	s_nop 1
	v_writelane_b32 v255, s3, 22
	s_add_u32 s2, s70, 0x2f80000
	s_addc_u32 s3, s71, 0
	s_add_u32 s20, s70, 0x144000
	v_writelane_b32 v255, s2, 23
	s_addc_u32 s21, s71, 0
	s_and_b64 s[0:1], s[22:23], s[0:1]
	v_writelane_b32 v255, s3, 24
	s_andn2_b64 vcc, exec, s[0:1]
	s_cbranch_vccnz .LBB0_641
	s_abs_i32 s2, s54
	v_cvt_f32_u32_e32 v2, s2
	s_sub_i32 s4, 0, s2
	s_ashr_i32 s3, s54, 31
	s_mov_b32 s38, 0
	v_rcp_iflag_f32_e32 v2, v2
	s_mov_b64 s[0:1], -1
	v_readfirstlane_b32 s39, v0
	v_mul_f32_e32 v2, 0x4f7ffffe, v2
	v_cvt_u32_f32_e32 v2, v2
	s_nop 0
	v_readfirstlane_b32 s5, v2
	s_mul_i32 s4, s4, s5
	s_mul_hi_u32 s4, s5, s4
	s_add_i32 s5, s5, s4
	s_mul_hi_u32 s4, s5, 0x110
	s_mul_i32 s5, s4, s2
	s_sub_i32 s5, 0x110, s5
	s_add_i32 s6, s4, 1
	s_sub_i32 s7, s5, s2
	s_cmp_ge_u32 s5, s2
	s_cselect_b32 s4, s6, s4
	s_cselect_b32 s5, s7, s5
	s_add_i32 s6, s4, 1
	s_cmp_ge_u32 s5, s2
	s_cselect_b32 s2, s6, s4
	s_xor_b32 s2, s2, s3
	s_sub_i32 s19, s2, s3
	s_mul_i32 s2, s19, s54
	s_sub_i32 s3, 0x110, s2
	s_cmpk_lg_i32 s2, 0x110
	s_cselect_b64 s[4:5], -1, 0
	s_lshl_b32 s18, s3, 3
	s_cmp_le_i32 s18, s54
	s_cselect_b64 s[6:7], -1, 0
	s_ashr_i32 s77, s56, 31
	s_and_b64 s[16:17], s[4:5], s[6:7]
	s_lshr_b32 s4, s77, 29
	s_add_i32 s4, s56, s4
	s_and_b32 s5, s4, -8
	s_xor_b64 s[78:79], s[16:17], -1
	s_sub_i32 s11, s56, s5
	s_ashr_i32 s33, s4, 3
	s_cmp_lt_i32 s11, 0
	s_cselect_b64 s[8:9], -1, 0
	s_cmpk_lt_i32 s56, 0x110
	s_cselect_b64 s[24:25], -1, 0
	s_and_b32 s3, s3, 7
	s_cmp_eq_u32 s3, 0
	s_cselect_b64 s[4:5], -1, 0
	s_ashr_i32 s6, s56, 3
	s_and_b32 s3, s56, 7
	s_and_b32 s28, s6, -8
	s_cmp_lt_i32 s56, s18
	s_cselect_b64 s[6:7], -1, 0
	v_writelane_b32 v255, s6, 25
	s_cmp_ge_i32 s56, s18
	s_cselect_b64 s[26:27], -1, 0
	v_writelane_b32 v255, s7, 26
	s_and_b64 vcc, exec, s[78:79]
	s_cbranch_vccz .LBB0_344
	s_mov_b64 s[0:1], 0
	s_andn2_b64 vcc, exec, s[24:25]
	s_mov_b64 s[6:7], 0
	s_cbranch_vccnz .LBB0_345
	s_and_b64 s[6:7], s[8:9], exec
	s_cselect_b32 s6, 35, 34
	s_mul_i32 s6, s11, s6
	s_add_i32 s6, s6, s33
	s_ashr_i32 s7, s6, 31
	s_lshr_b32 s7, s7, 27
	s_add_i32 s7, s6, s7
	s_ashr_i32 s10, s7, 5
	s_lshl_b32 s12, s10, 3
	s_sub_i32 s10, 0x44, s12
	s_andn2_b32 s7, s7, 31
	s_min_u32 s13, s10, 8
	s_sub_i32 s14, s6, s7
	s_sext_i32_i8 s6, s14
	v_cvt_f32_ubyte0_e32 v3, s13
	v_cvt_f32_i32_e32 v2, s6
	v_rcp_iflag_f32_e32 v4, v3
	s_ashr_i32 s6, s6, 30
	s_or_b32 s10, s6, 1
	v_mul_f32_e32 v4, v2, v4
	v_trunc_f32_e32 v4, v4
	v_fma_f32 v2, -v4, v3, v2
	v_cvt_i32_f32_e32 v4, v4
	v_cmp_ge_f32_e64 s[6:7], |v2|, v3
	s_and_b64 s[6:7], s[6:7], exec
	s_cselect_b32 s6, s10, 0
	v_readfirstlane_b32 s7, v4
	s_add_i32 s6, s7, s6
	s_sext_i32_i8 s10, s6
	s_mul_i32 s6, s6, s13
	s_sub_i32 s6, s14, s6
	s_sext_i32_i8 s6, s6
	s_add_i32 s76, s12, s6
	s_mov_b64 s[6:7], -1
	s_branch .LBB0_345

.Lcpf_skip_2:
	s_waitcnt lgkmcnt(0)
	s_barrier
.LBB0_692:
	s_cmp_lt_i32 s52, 4
	s_cselect_b64 s[36:37], -1, 0
	s_add_u32 s8, s70, 0x7600000
	s_addc_u32 s9, s71, 0
	s_add_u32 s4, s70, 0x9800000
	s_addc_u32 s5, s71, 0
	s_add_u32 s2, s70, 0xba00000
	s_addc_u32 s3, s71, 0
	s_add_u32 s42, s70, 0xdc00000
	v_writelane_b32 v255, s2, 29
	s_addc_u32 s43, s71, 0
	s_and_b64 s[0:1], s[36:37], s[0:1]
	v_writelane_b32 v255, s3, 30
	s_andn2_b64 vcc, exec, s[0:1]
	s_cbranch_vccnz .LBB0_872
	s_cmpk_gt_i32 s56, 0x32f
	s_cselect_b64 s[0:1], -1, 0
	s_mov_b32 s17, -1
	s_and_b64 vcc, exec, s[0:1]
	s_cbranch_vccnz .LBB0_695
	s_abs_i32 s2, s54
	v_cvt_f32_u32_e32 v2, s2
	s_sub_i32 s7, 0, s2
	s_sub_i32 s3, 0x32f, s56
	s_xor_b32 s6, s3, s54
	v_rcp_iflag_f32_e32 v2, v2
	s_abs_i32 s3, s3
	s_ashr_i32 s6, s6, 31
	v_mul_f32_e32 v2, 0x4f7ffffe, v2
	v_cvt_u32_f32_e32 v2, v2
	s_nop 0
	v_readfirstlane_b32 s10, v2
	s_mul_i32 s7, s7, s10
	s_mul_hi_u32 s7, s10, s7
	s_add_i32 s10, s10, s7
	s_mul_hi_u32 s7, s3, s10
	s_mul_i32 s10, s7, s2
	s_sub_i32 s3, s3, s10
	s_add_i32 s11, s7, 1
	s_sub_i32 s10, s3, s2
	s_cmp_ge_u32 s3, s2
	s_cselect_b32 s7, s11, s7
	s_cselect_b32 s3, s10, s3
	s_add_i32 s10, s7, 1
	s_cmp_ge_u32 s3, s2
	s_cselect_b32 s2, s10, s7
	s_xor_b32 s2, s2, s6
	s_sub_i32 s17, s2, s6

.LBB0_921:
	s_or_b64 exec, exec, s[0:1]
	v_readlane_b32 s98, v254, 61
	s_cmp_lg_u32 s98, 1
	s_cbranch_scc1 .Lcpf_skip_3
	s_getpc_b64 s[98:99]

.Lcpf_skip_3:
	s_waitcnt lgkmcnt(0)
	s_barrier
.LBB0_922:
	s_cmp_lt_i32 s52, 6
	s_cselect_b64 s[88:89], -1, 0
	s_cmp_gt_i32 s52, 5
	s_cselect_b64 s[0:1], -1, 0
	s_cmp_lt_i32 s53, 6
	s_cselect_b64 s[2:3], -1, 0
	s_or_b64 s[0:1], s[0:1], s[2:3]
	s_and_b64 vcc, exec, s[0:1]
	s_cbranch_vccnz .LBB0_1235
	s_abs_i32 s2, s54
	v_cvt_f32_u32_e32 v2, s2
	s_sub_i32 s7, 0, s2
	s_ashr_i32 s6, s54, 31
	s_mov_b32 s3, 0
	v_rcp_iflag_f32_e32 v2, v2
	s_mov_b64 s[0:1], -1
	v_readfirstlane_b32 s13, v0
	v_mul_f32_e32 v2, 0x4f7ffffe, v2
	v_cvt_u32_f32_e32 v2, v2
	s_nop 0
	v_readfirstlane_b32 s10, v2
	s_mul_i32 s7, s7, s10
	s_mul_hi_u32 s7, s10, s7
	s_add_i32 s10, s10, s7
	s_mul_hi_u32 s7, s10, 0x110
	s_mul_i32 s10, s7, s2
	s_sub_i32 s10, 0x110, s10
	s_add_i32 s11, s7, 1
	s_sub_i32 s12, s10, s2
	s_cmp_ge_u32 s10, s2
	s_cselect_b32 s7, s11, s7
	s_cselect_b32 s10, s12, s10
	s_add_i32 s11, s7, 1
	s_cmp_ge_u32 s10, s2
	s_cselect_b32 s2, s11, s7
	s_xor_b32 s2, s2, s6
	s_sub_i32 s2, s2, s6
	s_mov_b32 s22, s2
	s_mul_i32 s2, s2, s54
	s_sub_i32 s12, 0x110, s2
	s_cmpk_lg_i32 s2, 0x110
	s_cselect_b64 s[6:7], -1, 0
	s_lshl_b32 s36, s12, 3
	s_cmp_le_i32 s36, s54
	s_cselect_b64 s[10:11], -1, 0
	s_and_b64 s[44:45], s[6:7], s[10:11]
	s_xor_b64 s[10:11], s[44:45], -1
	s_and_b64 vcc, exec, s[10:11]
	s_cbranch_vccz .LBB0_931
	s_mov_b64 s[0:1], 0
	s_cmpk_gt_i32 s56, 0x10f
	s_mov_b64 s[6:7], 0
	s_cbranch_scc1 .LBB0_926
	s_ashr_i32 s6, s56, 31
	s_lshr_b32 s6, s6, 29
	s_add_i32 s6, s56, s6
	s_ashr_i32 s7, s6, 3
	s_and_b32 s6, s6, -8
	s_sub_i32 s6, s56, s6
	s_cmp_lt_i32 s6, 0
	s_cselect_b32 s14, 35, 34
	s_mul_i32 s6, s6, s14
	s_add_i32 s6, s6, s7
	s_ashr_i32 s7, s6, 31
	s_lshr_b32 s7, s7, 27
	s_add_i32 s7, s6, s7
	s_ashr_i32 s7, s7, 5
	s_lshl_b32 s14, s7, 3
	s_sub_i32 s15, 0x44, s14
	s_lshl_b32 s7, s7, 5
	s_min_u32 s15, s15, 8
	s_sub_i32 s16, s6, s7
	s_sext_i32_i8 s6, s16
	s_waitcnt lgkmcnt(0)
	v_cvt_f32_ubyte0_e32 v3, s15
	v_cvt_f32_i32_e32 v2, s6
	v_rcp_iflag_f32_e32 v4, v3
	s_ashr_i32 s6, s6, 30
	s_or_b32 s17, s6, 1
	v_mul_f32_e32 v4, v2, v4
	v_trunc_f32_e32 v4, v4
	v_fma_f32 v2, -v4, v3, v2
	v_cvt_i32_f32_e32 v4, v4
	v_cmp_ge_f32_e64 s[6:7], |v2|, v3
	s_and_b64 s[6:7], s[6:7], exec
	s_cselect_b32 s6, s17, 0
	v_readfirstlane_b32 s7, v4
	s_add_i32 s6, s7, s6
	s_sext_i32_i8 s24, s6
	s_mul_i32 s6, s6, s15
	s_sub_i32 s6, s16, s6
	s_sext_i32_i8 s6, s6
	s_add_i32 s26, s14, s6
	s_mov_b64 s[6:7], -1

.LBB0_1284:
	s_or_b64 exec, exec, s[6:7]
	v_readlane_b32 s98, v254, 61
	s_cmp_lg_u32 s98, 1
	s_cbranch_scc1 .Lcpf_skip_4
	s_getpc_b64 s[98:99]

.Lcpf_skip_4:
	s_waitcnt lgkmcnt(0)
	s_barrier
.LBB0_1285:
	s_cmp_lt_i32 s52, 7
	s_cselect_b64 s[20:21], -1, 0
	s_and_b64 s[0:1], s[20:21], s[0:1]
	s_andn2_b64 vcc, exec, s[0:1]
	s_cbranch_vccnz .LBB0_1360
	s_abs_i32 s0, s54
	v_cvt_f32_u32_e32 v2, s0
	s_sub_i32 s2, 0, s0
	s_ashr_i32 s1, s54, 31
	s_mov_b32 s52, 0
	v_rcp_iflag_f32_e32 v2, v2
	s_mov_b64 s[16:17], -1
	v_readfirstlane_b32 s33, v0
	v_mul_f32_e32 v2, 0x4f7ffffe, v2
	v_cvt_u32_f32_e32 v2, v2
	s_nop 0
	v_readfirstlane_b32 s3, v2
	s_mul_i32 s2, s2, s3
	s_mul_hi_u32 s2, s3, s2
	s_add_i32 s3, s3, s2
	s_mul_hi_u32 s2, s3, 0x220
	s_mul_i32 s3, s2, s0
	s_sub_i32 s3, 0x220, s3
	s_add_i32 s6, s2, 1
	s_sub_i32 s7, s3, s0
	s_cmp_ge_u32 s3, s0
	s_cselect_b32 s2, s6, s2
	s_cselect_b32 s3, s7, s3
	s_add_i32 s6, s2, 1
	s_cmp_ge_u32 s3, s0
	s_cselect_b32 s0, s6, s2
	s_xor_b32 s0, s0, s1
	s_sub_i32 s0, s0, s1
	s_mul_i32 s2, s0, s54
	s_sub_i32 s3, 0x220, s2
	s_cmpk_lg_i32 s2, 0x220
	v_writelane_b32 v255, s0, 10
	s_cselect_b64 s[0:1], -1, 0
	s_lshl_b32 s12, s3, 3
	s_cmp_le_i32 s12, s54
	s_cselect_b64 s[6:7], -1, 0
	s_ashr_i32 s8, s56, 31
	s_and_b64 s[0:1], s[0:1], s[6:7]
	s_lshr_b32 s6, s8, 29
	s_add_i32 s6, s56, s6
	s_and_b32 s7, s6, -8
	v_writelane_b32 v255, s8, 19
	s_xor_b64 s[8:9], s[0:1], -1
	s_sub_i32 s10, s56, s7
	s_ashr_i32 s11, s6, 3
	s_cmp_lt_i32 s10, 0
	s_cselect_b64 s[26:27], -1, 0
	s_cmpk_lt_i32 s56, 0x220
	s_cselect_b64 s[28:29], -1, 0
	s_and_b32 s6, s56, 7
	s_and_b32 s3, s3, 7
	s_cmp_eq_u32 s3, 0
	s_cselect_b64 s[34:35], -1, 0
	s_ashr_i32 s3, s56, 3
	s_and_b32 s3, s3, -8
	s_cmp_lt_i32 s56, s12
	s_cselect_b64 s[14:15], -1, 0
	v_writelane_b32 v255, s14, 17
	s_cmp_ge_i32 s56, s12
	s_cselect_b64 s[30:31], -1, 0
	v_writelane_b32 v255, s15, 18
	s_and_b64 vcc, exec, s[8:9]
	s_cbranch_vccz .LBB0_1289
	s_mov_b64 s[16:17], 0
	s_andn2_b64 vcc, exec, s[28:29]
	s_mov_b64 s[24:25], 0
	s_cbranch_vccnz .LBB0_1290
	s_movk_i32 s7, 0x45
	s_and_b64 s[12:13], s[26:27], exec
	s_cselect_b32 s7, s7, 0x44
	s_mul_i32 s7, s10, s7
	s_add_i32 s7, s7, s11
	s_ashr_i32 s12, s7, 31
	s_lshr_b32 s12, s12, 26
	s_add_i32 s12, s7, s12
	s_ashr_i32 s13, s12, 6
	s_lshl_b32 s15, s13, 3
	s_sub_i32 s13, 0x44, s15
	s_andn2_b32 s12, s12, 63
	s_min_u32 s18, s13, 8
	s_sub_i32 s7, s7, s12
	s_sext_i32_i8 s12, s7
	s_waitcnt lgkmcnt(0)
	v_cvt_f32_ubyte0_e32 v3, s18
	v_cvt_f32_i32_e32 v2, s12
	v_rcp_iflag_f32_e32 v4, v3
	s_ashr_i32 s12, s12, 30
	s_or_b32 s14, s12, 1
	s_mov_b64 s[24:25], -1
	v_mul_f32_e32 v4, v2, v4
	v_trunc_f32_e32 v4, v4
	v_fma_f32 v2, -v4, v3, v2
	v_cvt_i32_f32_e32 v4, v4
	v_cmp_ge_f32_e64 s[12:13], |v2|, v3
	s_and_b64 s[12:13], s[12:13], exec
	s_cselect_b32 s12, s14, 0
	v_readfirstlane_b32 s13, v4
	s_add_i32 s12, s13, s12
	s_sext_i32_i8 s14, s12
	s_mul_i32 s12, s12, s18
	s_sub_i32 s7, s7, s12
	s_sext_i32_i8 s7, s7
	s_add_i32 s12, s15, s7
	s_branch .LBB0_1290

.Lcpf_skip_5:
	s_waitcnt lgkmcnt(0)
	s_barrier
.LBB0_1411:
	s_cmp_lt_i32 s36, 8
	s_cselect_b64 s[2:3], -1, 0
	s_add_u32 s8, s70, 0x188000
	s_addc_u32 s9, s71, 0
	v_writelane_b32 v255, s2, 37
	s_and_b64 s[0:1], s[2:3], s[0:1]
	s_andn2_b64 vcc, exec, s[0:1]
	v_writelane_b32 v255, s3, 38
	s_cbranch_vccnz .LBB0_1656
	s_abs_i32 s2, s54
	v_cvt_f32_u32_e32 v2, s2
	s_sub_i32 s4, 0, s2
	s_ashr_i32 s3, s54, 31
	s_mov_b32 s96, 0
	v_rcp_iflag_f32_e32 v2, v2
	s_mov_b64 s[0:1], -1
	v_mul_f32_e32 v2, 0x4f7ffffe, v2
	v_cvt_u32_f32_e32 v2, v2
	s_nop 0
	v_readfirstlane_b32 s5, v2
	s_mul_i32 s4, s4, s5
	s_mul_hi_u32 s4, s5, s4
	s_add_i32 s5, s5, s4
	s_mul_hi_u32 s4, s5, 0x110
	s_mul_i32 s5, s4, s2
	s_sub_i32 s5, 0x110, s5
	s_add_i32 s6, s4, 1
	s_sub_i32 s7, s5, s2
	s_cmp_ge_u32 s5, s2
	s_cselect_b32 s4, s6, s4
	s_cselect_b32 s5, s7, s5
	s_add_i32 s6, s4, 1
	s_cmp_ge_u32 s5, s2
	s_cselect_b32 s2, s6, s4
	s_xor_b32 s2, s2, s3
	s_sub_i32 s2, s2, s3
	s_mul_i32 s3, s2, s54
	s_sub_i32 s6, 0x110, s3
	s_cmpk_lg_i32 s3, 0x110
	s_cselect_b64 s[4:5], -1, 0
	s_lshl_b32 s20, s6, 3
	s_cmp_le_i32 s20, s54
	s_cselect_b64 s[10:11], -1, 0
	s_and_b64 s[36:37], s[4:5], s[10:11]
	s_xor_b64 s[16:17], s[36:37], -1
	s_mov_b32 s22, s2
	v_readfirstlane_b32 s2, v0
	s_and_b64 vcc, exec, s[16:17]
	s_cbranch_vccz .LBB0_1420
	s_mov_b64 s[0:1], 0
	s_cmpk_gt_i32 s56, 0x10f
	s_mov_b64 s[4:5], 0
	s_cbranch_scc1 .LBB0_1415
	s_ashr_i32 s4, s56, 31
	s_lshr_b32 s4, s4, 29
	s_add_i32 s4, s56, s4
	s_ashr_i32 s5, s4, 3
	s_and_b32 s4, s4, -8
	s_sub_i32 s4, s56, s4
	s_cmp_lt_i32 s4, 0
	s_cselect_b32 s7, 35, 34
	s_mul_i32 s4, s4, s7
	s_add_i32 s4, s4, s5
	s_ashr_i32 s5, s4, 31
	s_lshr_b32 s5, s5, 27
	s_add_i32 s5, s4, s5
	s_ashr_i32 s5, s5, 5
	s_lshl_b32 s7, s5, 3
	s_sub_i32 s10, 0x44, s7
	s_lshl_b32 s5, s5, 5
	s_min_u32 s11, s10, 8
	s_sub_i32 s12, s4, s5
	s_sext_i32_i8 s4, s12
	s_waitcnt lgkmcnt(0)
	v_cvt_f32_ubyte0_e32 v3, s11
	v_cvt_f32_i32_e32 v2, s4
	v_rcp_iflag_f32_e32 v4, v3
	s_ashr_i32 s4, s4, 30
	s_or_b32 s10, s4, 1
	v_mul_f32_e32 v4, v2, v4
	v_trunc_f32_e32 v4, v4
	v_fma_f32 v2, -v4, v3, v2
	v_cvt_i32_f32_e32 v4, v4
	v_cmp_ge_f32_e64 s[4:5], |v2|, v3
	s_and_b64 s[4:5], s[4:5], exec
	s_cselect_b32 s4, s10, 0
	v_readfirstlane_b32 s5, v4
	s_add_i32 s4, s5, s4
	s_sext_i32_i8 s10, s4
	s_mul_i32 s4, s4, s11
	s_sub_i32 s4, s12, s4
	s_sext_i32_i8 s4, s4
	s_add_i32 s24, s7, s4
	s_mov_b64 s[4:5], -1

.Lcpf_skip_6:
	s_waitcnt lgkmcnt(0)
	s_barrier
.LBB0_1706:
	s_cmp_lt_i32 s36, 9
	s_cselect_b64 s[48:49], -1, 0
	s_and_b64 s[0:1], s[48:49], s[0:1]
	s_andn2_b64 vcc, exec, s[0:1]
	s_cbranch_vccnz .LBB0_2037
	s_abs_i32 s2, s54
	v_cvt_f32_u32_e32 v2, s2
	s_sub_i32 s0, 0, s2
	v_rcp_iflag_f32_e32 v2, v2
	s_nop 0
	v_mul_f32_e32 v2, 0x4f7ffffe, v2
	v_cvt_u32_f32_e32 v2, v2
	s_nop 0
	v_readfirstlane_b32 s1, v2
	s_mul_i32 s0, s0, s1
	s_mul_hi_u32 s0, s1, s0
	s_add_i32 s1, s1, s0
	s_mul_hi_u32 s0, s1, 0x5d8
	s_cmpk_gt_i32 s56, 0x5d7
	v_readfirstlane_b32 s1, v0
	s_cbranch_scc1 .LBB0_1730
	v_lshlrev_b32_e32 v2, 4, v0
	s_waitcnt lgkmcnt(0)
	v_and_b32_e32 v3, 32, v0
	v_lshrrev_b32_e32 v4, 3, v0
	s_waitcnt vmcnt(0)
	v_bfe_u32 v6, v0, 2, 4
	v_lshrrev_b32_e32 v9, 1, v0
	v_lshrrev_b32_e32 v10, 5, v0
	v_bfe_u32 v11, v0, 2, 2
	v_writelane_b32 v255, s0, 23
	v_and_or_b32 v5, v4, 48, v6
	v_bitop3_b32 v7, v2, v3, 48 bitop3:0x6c
	v_and_b32_e32 v8, 64, v0
	v_and_b32_e32 v4, 32, v4
	v_and_b32_e32 v9, 24, v9
	v_and_or_b32 v10, v10, 4, v11
	s_movk_i32 s0, 0x60
	s_ashr_i32 s53, s56, 31
	v_or3_b32 v4, v10, v4, v9
	v_bitop3_b32 v10, v7, s0, v8 bitop3:0xc8
	s_lshr_b32 s0, s53, 29
	s_add_i32 s0, s56, s0
	s_lshr_b32 s4, s1, 6
	s_ashr_i32 s5, s0, 3
	s_and_b32 s0, s0, -8
	s_lshr_b32 s3, s1, 8
	s_lshl_b32 s52, s4, 10
	s_sub_i32 s0, s56, s0
	s_cmp_lt_i32 s0, 0
	s_movk_i32 s76, 0xbc
	s_cselect_b32 s6, s76, 0xbb
	s_mul_i32 s0, s0, s6
	s_add_i32 s0, s0, s5
	s_mul_hi_i32 s5, s0, 0x2e8ba2e9
	s_lshr_b32 s6, s5, 31
	s_ashr_i32 s5, s5, 5
	s_add_i32 s5, s5, s6
	s_lshl_b32 s10, s5, 3
	s_sub_i32 s6, 0x44, s10
	v_or_b32_e32 v3, v7, v8
	s_min_u32 s11, s6, 8
	s_mulk_i32 s5, 0xb0
	v_lshl_or_b32 v132, v4, 11, v3
	s_sub_i32 s5, s0, s5
	v_cvt_f32_ubyte0_e32 v3, s11
	v_and_b32_e32 v9, 16, v2
	v_cvt_f32_i32_e32 v2, s5
	v_rcp_iflag_f32_e32 v4, v3
	s_ashr_i32 s0, s5, 30
	s_or_b32 s0, s0, 1
	v_and_b32_e32 v142, 0xff, v0
	v_mul_f32_e32 v4, v2, v4
	v_trunc_f32_e32 v4, v4
	v_fma_f32 v2, -v4, v3, v2
	v_cvt_i32_f32_e32 v4, v4
	v_cmp_ge_f32_e64 s[6:7], |v2|, v3
	s_and_b64 s[6:7], s[6:7], exec
	s_cselect_b32 s0, s0, 0
	v_readfirstlane_b32 s6, v4
	s_add_i32 s0, s6, s0
	s_mul_i32 s6, s0, s11
	s_sub_i32 s5, s5, s6
	s_sext_i32_i16 s5, s5
	s_add_i32 s10, s10, s5
	v_readfirstlane_b32 s5, v0
	s_lshl_b32 s5, s5, 4
	s_and_b32 s5, s5, 0xc00
	s_add_i32 s5, s5, 0
	s_ashr_i32 s11, s10, 31
	s_add_i32 m0, s5, 0x22000
	s_lshl_b64 s[6:7], s[10:11], 19
	s_add_u32 s14, s42, s6
	s_addc_u32 s15, s43, s7
	s_bfe_i64 s[6:7], s[0:1], 0x100000
	v_lshl_or_b32 v2, s10, 8, v142
	s_lshl_b64 s[6:7], s[6:7], 19
	v_readlane_b32 s12, v255, 15
	v_ashrrev_i32_e32 v3, 31, v2
	v_readlane_b32 s13, v255, 16
	s_add_u32 s6, s12, s6
	v_mov_b32_e32 v133, 0
	v_lshl_add_u64 v[2:3], v[2:3], 4, s[8:9]
	s_addc_u32 s7, s13, s7
	s_add_i32 s11, s52, 0
	v_lshlrev_b32_e32 v5, 11, v5
	global_load_lds_dwordx4 v[2:3], off
	v_lshl_add_u64 v[2:3], s[6:7], 0, v[132:133]
	s_add_i32 m0, s11, 0x10000
	s_mov_b64 s[16:17], 0x20000
	v_or3_b32 v130, v10, v5, v9
	global_load_lds_dwordx4 v132, s[6:7]
	v_lshl_add_u64 v[4:5], v[2:3], 0, s[16:17]
	s_add_i32 m0, s11, 0x12000
	s_mov_b64 s[24:25], 0x40000
	global_load_lds_dwordx4 v[4:5], off
	v_lshl_add_u64 v[4:5], v[2:3], 0, s[24:25]
	s_add_i32 m0, s11, 0x14000
	s_mov_b64 s[26:27], 0x60000
	v_mov_b32_e32 v131, v133
	global_load_lds_dwordx4 v[4:5], off
	v_lshl_add_u64 v[4:5], v[2:3], 0, s[26:27]
	s_add_i32 m0, s11, 0x16000
	s_add_i32 s77, s11, 0x2000
	global_load_lds_dwordx4 v[4:5], off
	v_lshl_add_u64 v[4:5], s[14:15], 0, v[130:131]
	s_mov_b32 m0, s11
	v_lshl_add_u64 v[10:11], v[4:5], 0, s[16:17]
	global_load_lds_dwordx4 v130, s[14:15]
	s_mov_b32 m0, s77
	s_add_i32 s80, s11, 0x4000
	global_load_lds_dwordx4 v[10:11], off
	v_lshl_add_u64 v[10:11], v[4:5], 0, s[24:25]
	s_mov_b32 m0, s80
	s_add_i32 s81, s11, 0x6000
	global_load_lds_dwordx4 v[10:11], off
	v_lshl_add_u64 v[10:11], v[4:5], 0, s[26:27]
	s_mov_b32 m0, s81
	s_cmp_eq_u32 s3, 1
	global_load_lds_dwordx4 v[10:11], off
	s_mov_b64 s[22:23], s[48:49]
	s_cselect_b64 s[28:29], -1, 0
	s_cmp_lg_u32 s3, 1
	s_cbranch_scc1 .LBB0_1710
	s_barrier

.Lcpf_pc_7:
	s_add_u32 s98, s98, .LBB0_2087-.Lcpf_pc_7
	s_addc_u32 s99, s99, 0
	v_lshlrev_b32_e32 v252, 7, v186
	global_load_dword v253, v252, s[98:99]
	s_add_u32 s98, s98, 0x2000
	s_addc_u32 s99, s99, 0
	global_load_dword v253, v252, s[98:99]
.Lcpf_skip_7:
	s_waitcnt lgkmcnt(0)
	s_barrier
.LBB0_2087:
	s_cmp_lt_i32 s36, 10
	s_cselect_b64 s[4:5], -1, 0
	s_cmpk_eq_i32 s54, 0x100
	s_cselect_b64 s[2:3], -1, 0
	s_and_b64 s[0:1], s[0:1], s[2:3]
	s_and_b64 s[0:1], s[4:5], s[0:1]
	s_andn2_b64 vcc, exec, s[0:1]
	s_cbranch_vccnz .LBB0_2201
	s_cmpk_lt_i32 s56, 0x80
	s_cselect_b64 s[14:15], -1, 0
	s_cmpk_gt_i32 s56, 0x7f
	v_readfirstlane_b32 s3, v0
	s_cbranch_scc0 .LBB0_2091
	s_cmpk_lt_u32 s56, 0x100
	s_cbranch_scc1 .LBB0_2092
	s_add_i32 s0, s56, 0xffffff00
	s_lshr_b32 s0, s0, 2
	s_add_i32 s72, s0, 64
	s_and_b32 s16, s56, 3
	s_cbranch_execz .LBB0_2093
	s_branch .LBB0_2094

.Lcpf_pc_8:
	s_add_u32 s98, s98, .LBB0_2251-.Lcpf_pc_8
	s_addc_u32 s99, s99, 0
	v_lshlrev_b32_e32 v252, 7, v186
	global_load_dword v253, v252, s[98:99]
.Lcpf_skip_8:
	s_waitcnt lgkmcnt(0)
	s_barrier
.LBB0_2251:
	s_endpgm
